# SGU item: gate-row and bias loads of the position pass issued before the VT build (latency overlapped), on top of the read2 split
# speedup vs baseline: 1.0081x; 1.0031x over previous
.LBB0_249:
	s_or_b64 exec, exec, s[8:9]
	v_lshl_add_u32 v50, v73, 1, 0
	s_movk_i32 s14, 0x110
	v_cvt_pk_bf16_f32 v22, v22, v23
	v_cvt_pk_bf16_f32 v23, v24, v25
	v_cvt_pk_bf16_f32 v24, v18, v19
	s_waitcnt lgkmcnt(1)
	v_mad_u64_u32 v[18:19], s[8:9], v74, s14, v[50:51]
	v_cvt_pk_bf16_f32 v25, v20, v21
	ds_write_b128 v18, v[22:25]
	v_mad_u64_u32 v[22:23], s[8:9], v71, s14, v[50:51]
	v_cvt_pk_bf16_f32 v18, v30, v31
	v_cvt_pk_bf16_f32 v19, v32, v33
	v_cvt_pk_bf16_f32 v20, v26, v27
	v_cvt_pk_bf16_f32 v21, v28, v29
	ds_write_b128 v22, v[18:21]
	v_mad_u64_u32 v[22:23], s[8:9], v70, s14, v[50:51]
	v_cvt_pk_bf16_f32 v18, v38, v39
	v_cvt_pk_bf16_f32 v19, v40, v41
	v_cvt_pk_bf16_f32 v20, v34, v35
	v_cvt_pk_bf16_f32 v21, v36, v37
	ds_write_b128 v22, v[18:21]
	v_mad_u64_u32 v[22:23], s[8:9], v69, s14, v[50:51]
	v_cvt_pk_bf16_f32 v18, v46, v47
	v_cvt_pk_bf16_f32 v19, v48, v49
	v_cvt_pk_bf16_f32 v20, v42, v43
	v_cvt_pk_bf16_f32 v21, v44, v45
	ds_write_b128 v22, v[18:21]
	s_waitcnt lgkmcnt(0)
	s_barrier
	s_load_dwordx2 s[8:9], s[0:1], 0xa0
	s_load_dwordx2 s[42:43], s[0:1], 0xb0
	v_readlane_b32 s16, v255, 38
	v_readlane_b32 s17, v255, 39
	s_lshl_b64 s[12:13], s[16:17], 2
	v_and_b32_e32 v26, 0xffff0000, v14
	s_waitcnt lgkmcnt(0)
	s_add_u32 s8, s8, s12
	s_addc_u32 s9, s9, s13
	s_lshl_b32 s12, s7, 2
	s_add_u32 s8, s8, s12
	s_addc_u32 s9, s9, 0
	global_load_dwordx4 v[22:25], v0, s[8:9]
	global_load_dwordx4 v[18:21], v0, s[8:9] offset:16
	v_and_b32_e32 v156, 15, v68
	v_bfe_u32 v157, v68, 4, 2
	v_and_b32_e32 v158, -16, v72
	v_lshl_or_b32 v158, v157, 2, v158
	v_ashrrev_i32_e32 v159, 31, v158
	v_mov_b32_e32 v160, s20
	v_mov_b32_e32 v161, 0
	v_lshl_add_u64 v[162:163], v[158:159], 1, v[160:161]
	s_add_i32 s98, s11, 16
	v_add_lshl_u32 v160, s98, v156, 11
	v_lshl_add_u64 v[164:165], v[162:163], 0, v[160:161]
	s_lshl_b32 s98, s10, 16
	s_and_b32 s98, s98, 0x3fc0000
	v_lshl_or_b32 v160, v156, 11, s98
	v_lshl_add_u64 v[162:163], v[162:163], 0, v[160:161]
	v_lshl_add_u64 v[164:165], s[64:65], 0, v[164:165]
	v_lshl_add_u64 v[162:163], s[64:65], 0, v[162:163]
	s_add_i32 s98, s16, s7
	v_add_u32_e32 v166, s98, v156
	v_ashrrev_i32_e32 v167, 31, v166
	v_lshl_add_u64 v[166:167], v[166:167], 2, s[42:43]
	global_load_dword v80, v[166:167], off
	global_load_dword v81, v[166:167], off offset:64
	global_load_dword v82, v[166:167], off offset:128
	global_load_dword v83, v[166:167], off offset:192
	global_load_dword v84, v[166:167], off offset:256
	global_load_dword v85, v[166:167], off offset:320
	global_load_dword v86, v[166:167], off offset:384
	global_load_dword v87, v[166:167], off offset:448
	s_mov_b32 s98, 0xc200000
	s_mov_b32 s99, 0
	v_lshl_add_u64 v[160:161], v[162:163], 0, s[98:99]
	global_load_dwordx2 v[88:89], v[160:161], off
	v_lshl_add_u64 v[160:161], v[164:165], 0, s[98:99]
	global_load_dwordx2 v[90:91], v[160:161], off
	s_add_u32 s98, s98, 0x10000
	v_lshl_add_u64 v[160:161], v[162:163], 0, s[98:99]
	global_load_dwordx2 v[92:93], v[160:161], off
	v_lshl_add_u64 v[160:161], v[164:165], 0, s[98:99]
	global_load_dwordx2 v[94:95], v[160:161], off
	s_add_u32 s98, s98, 0x10000
	v_lshl_add_u64 v[160:161], v[162:163], 0, s[98:99]
	global_load_dwordx2 v[96:97], v[160:161], off
	v_lshl_add_u64 v[160:161], v[164:165], 0, s[98:99]
	global_load_dwordx2 v[98:99], v[160:161], off
	s_add_u32 s98, s98, 0x10000
	v_lshl_add_u64 v[160:161], v[162:163], 0, s[98:99]
	global_load_dwordx2 v[100:101], v[160:161], off
	v_lshl_add_u64 v[160:161], v[164:165], 0, s[98:99]
	global_load_dwordx2 v[102:103], v[160:161], off
	s_nop 0
	s_nop 0
	s_add_i32 s12, 0, 0x20000
	v_lshlrev_b32_e32 v0, 16, v14
	v_lshl_add_u32 v14, v74, 2, s12
	v_lshlrev_b32_e32 v27, 16, v15
	v_and_b32_e32 v28, 0xffff0000, v15
	ds_read2st64_b32 v[14:15], v14 offset1:2
	v_lshlrev_b32_e32 v29, 16, v16
	v_and_b32_e32 v16, 0xffff0000, v16
	v_lshlrev_b32_e32 v30, 16, v17
	v_and_b32_e32 v17, 0xffff0000, v17
	s_waitcnt lgkmcnt(0)
	v_sub_f32_e32 v0, v0, v14
	v_sub_f32_e32 v26, v26, v14
	v_sub_f32_e32 v27, v27, v14
	v_sub_f32_e32 v28, v28, v14
	v_sub_f32_e32 v29, v29, v14
	v_sub_f32_e32 v16, v16, v14
	v_sub_f32_e32 v30, v30, v14
	v_sub_f32_e32 v14, v17, v14
	v_mul_f32_e32 v0, v15, v0
	v_mul_f32_e32 v17, v15, v26
	v_mul_f32_e32 v26, v15, v27
	v_mul_f32_e32 v27, v15, v28
	v_mul_f32_e32 v28, v15, v29
	v_mul_f32_e32 v16, v15, v16
	v_mul_f32_e32 v29, v15, v30
	v_mul_f32_e32 v14, v15, v14
	v_xor_b32_e32 v31, v74, v73
	v_lshlrev_b32_e32 v31, 1, v31
	v_mul_u32_u24_e32 v32, 0x110, v73
	v_add3_u32 v31, 0, v31, v32
	s_load_dwordx2 s[8:9], s[0:1], 0xb0
	s_add_i32 s11, s11, 16
	s_lshl_b32 s6, s6, 7
	s_waitcnt vmcnt(17)
	v_mul_f32_e32 v0, v22, v0
	v_mul_f32_e32 v15, v23, v17
	v_mul_f32_e32 v17, v24, v26
	v_mul_f32_e32 v26, v25, v27
	s_waitcnt vmcnt(16)
	v_mul_f32_e32 v27, v18, v28
	v_mul_f32_e32 v16, v19, v16
	v_mul_f32_e32 v28, v20, v29
	v_mul_f32_e32 v29, v21, v14
	v_bfe_u32 v14, v0, 16, 1
	v_bfe_u32 v30, v15, 16, 1
	v_bfe_u32 v33, v17, 16, 1
	v_bfe_u32 v34, v26, 16, 1
	v_bfe_u32 v35, v27, 16, 1
	v_bfe_u32 v36, v16, 16, 1
	v_add3_u32 v0, v0, v14, s90
	v_add3_u32 v14, v15, v30, s90
	v_add3_u32 v15, v17, v33, s90
	v_add3_u32 v17, v26, v34, s90
	v_add3_u32 v26, v27, v35, s90
	v_add3_u32 v16, v16, v36, s90
	ds_write_b16_d16_hi v31, v0 offset:34816
	ds_write_b16_d16_hi v31, v14 offset:35088
	ds_write_b16_d16_hi v31, v15 offset:35360
	ds_write_b16_d16_hi v31, v17 offset:35632
	ds_write_b16_d16_hi v31, v26 offset:35904
	ds_write_b16_d16_hi v31, v16 offset:36176
	v_bfe_u32 v0, v28, 16, 1
	v_add3_u32 v0, v28, v0, s90
	ds_write_b16_d16_hi v31, v0 offset:36448
	v_lshl_add_u32 v0, v71, 2, s12
	ds_read2st64_b32 v[14:15], v0 offset1:2
	v_bfe_u32 v0, v29, 16, 1
	v_add3_u32 v0, v29, v0, s90
	ds_write_b16_d16_hi v31, v0 offset:36720
	v_lshlrev_b32_e32 v0, 16, v10
	s_waitcnt lgkmcnt(0)
	v_sub_f32_e32 v0, v0, v14
	v_mul_f32_e32 v0, v15, v0
	v_and_b32_e32 v10, 0xffff0000, v10
	v_lshlrev_b32_e32 v16, 16, v11
	v_and_b32_e32 v11, 0xffff0000, v11
	v_lshlrev_b32_e32 v17, 16, v12
	v_and_b32_e32 v12, 0xffff0000, v12
	v_lshlrev_b32_e32 v26, 16, v13
	v_and_b32_e32 v13, 0xffff0000, v13
	v_mul_f32_e32 v0, v22, v0
	v_sub_f32_e32 v10, v10, v14
	v_sub_f32_e32 v16, v16, v14
	v_sub_f32_e32 v11, v11, v14
	v_sub_f32_e32 v17, v17, v14
	v_sub_f32_e32 v12, v12, v14
	v_sub_f32_e32 v26, v26, v14
	v_sub_f32_e32 v13, v13, v14
	v_mul_f32_e32 v10, v15, v10
	v_mul_f32_e32 v16, v15, v16
	v_mul_f32_e32 v11, v15, v11
	v_mul_f32_e32 v17, v15, v17
	v_mul_f32_e32 v12, v15, v12
	v_mul_f32_e32 v26, v15, v26
	v_mul_f32_e32 v13, v15, v13
	v_xor_b32_e32 v14, v71, v73
	v_lshlrev_b32_e32 v14, 1, v14
	v_bfe_u32 v15, v0, 16, 1
	v_mul_f32_e32 v10, v23, v10
	v_add3_u32 v0, v0, v15, s90
	v_add3_u32 v14, 0, v14, v32
	ds_write_b16_d16_hi v14, v0 offset:34816
	v_bfe_u32 v0, v10, 16, 1
	v_mul_f32_e32 v16, v24, v16
	v_add3_u32 v0, v10, v0, s90
	ds_write_b16_d16_hi v14, v0 offset:35088
	v_bfe_u32 v0, v16, 16, 1
	v_mul_f32_e32 v11, v25, v11
	v_add3_u32 v0, v16, v0, s90
	ds_write_b16_d16_hi v14, v0 offset:35360
	v_bfe_u32 v0, v11, 16, 1
	v_mul_f32_e32 v17, v18, v17
	v_add3_u32 v0, v11, v0, s90
	ds_write_b16_d16_hi v14, v0 offset:35632
	v_bfe_u32 v0, v17, 16, 1
	v_mul_f32_e32 v12, v19, v12
	v_add3_u32 v0, v17, v0, s90
	ds_write_b16_d16_hi v14, v0 offset:35904
	v_bfe_u32 v0, v12, 16, 1
	v_mul_f32_e32 v26, v20, v26
	v_add3_u32 v0, v12, v0, s90
	ds_write_b16_d16_hi v14, v0 offset:36176
	v_bfe_u32 v0, v26, 16, 1
	v_add3_u32 v0, v26, v0, s90
	ds_write_b16_d16_hi v14, v0 offset:36448
	v_lshl_add_u32 v0, v70, 2, s12
	ds_read2st64_b32 v[10:11], v0 offset1:2
	v_mul_f32_e32 v13, v21, v13
	v_bfe_u32 v0, v13, 16, 1
	v_add3_u32 v0, v13, v0, s90
	ds_write_b16_d16_hi v14, v0 offset:36720
	v_lshlrev_b32_e32 v0, 16, v6
	s_waitcnt lgkmcnt(1)
	v_sub_f32_e32 v0, v0, v10
	v_mul_f32_e32 v0, v11, v0
	v_and_b32_e32 v6, 0xffff0000, v6
	v_lshlrev_b32_e32 v12, 16, v7
	v_and_b32_e32 v7, 0xffff0000, v7
	v_lshlrev_b32_e32 v13, 16, v8
	v_and_b32_e32 v8, 0xffff0000, v8
	v_lshlrev_b32_e32 v14, 16, v9
	v_and_b32_e32 v9, 0xffff0000, v9
	v_mul_f32_e32 v0, v22, v0
	v_sub_f32_e32 v6, v6, v10
	v_sub_f32_e32 v12, v12, v10
	v_sub_f32_e32 v7, v7, v10
	v_sub_f32_e32 v13, v13, v10
	v_sub_f32_e32 v8, v8, v10
	v_sub_f32_e32 v14, v14, v10
	v_sub_f32_e32 v9, v9, v10
	v_mul_f32_e32 v6, v11, v6
	v_mul_f32_e32 v12, v11, v12
	v_mul_f32_e32 v7, v11, v7
	v_mul_f32_e32 v13, v11, v13
	v_mul_f32_e32 v8, v11, v8
	v_mul_f32_e32 v14, v11, v14
	v_mul_f32_e32 v9, v11, v9
	v_xor_b32_e32 v10, v70, v73
	v_lshlrev_b32_e32 v10, 1, v10
	v_bfe_u32 v11, v0, 16, 1
	v_mul_f32_e32 v6, v23, v6
	v_add3_u32 v0, v0, v11, s90
	v_add3_u32 v10, 0, v10, v32
	ds_write_b16_d16_hi v10, v0 offset:34816
	v_bfe_u32 v0, v6, 16, 1
	v_mul_f32_e32 v12, v24, v12
	v_add3_u32 v0, v6, v0, s90
	ds_write_b16_d16_hi v10, v0 offset:35088
	v_bfe_u32 v0, v12, 16, 1
	v_mul_f32_e32 v7, v25, v7
	v_add3_u32 v0, v12, v0, s90
	ds_write_b16_d16_hi v10, v0 offset:35360
	v_bfe_u32 v0, v7, 16, 1
	v_mul_f32_e32 v13, v18, v13
	v_add3_u32 v0, v7, v0, s90
	ds_write_b16_d16_hi v10, v0 offset:35632
	v_bfe_u32 v0, v13, 16, 1
	v_mul_f32_e32 v8, v19, v8
	v_add3_u32 v0, v13, v0, s90
	ds_write_b16_d16_hi v10, v0 offset:35904
	v_bfe_u32 v0, v8, 16, 1
	v_mul_f32_e32 v14, v20, v14
	v_add3_u32 v0, v8, v0, s90
	ds_write_b16_d16_hi v10, v0 offset:36176
	v_bfe_u32 v0, v14, 16, 1
	v_add3_u32 v0, v14, v0, s90
	ds_write_b16_d16_hi v10, v0 offset:36448
	v_lshl_add_u32 v0, v69, 2, s12
	ds_read2st64_b32 v[6:7], v0 offset1:2
	v_mul_f32_e32 v9, v21, v9
	v_bfe_u32 v0, v9, 16, 1
	v_add3_u32 v0, v9, v0, s90
	ds_write_b16_d16_hi v10, v0 offset:36720
	v_lshlrev_b32_e32 v0, 16, v2
	s_waitcnt lgkmcnt(1)
	v_sub_f32_e32 v0, v0, v6
	v_mul_f32_e32 v0, v7, v0
	v_and_b32_e32 v2, 0xffff0000, v2
	v_lshlrev_b32_e32 v8, 16, v3
	v_and_b32_e32 v3, 0xffff0000, v3
	v_lshlrev_b32_e32 v9, 16, v4
	v_and_b32_e32 v4, 0xffff0000, v4
	v_lshlrev_b32_e32 v10, 16, v5
	v_and_b32_e32 v5, 0xffff0000, v5
	v_mul_f32_e32 v0, v22, v0
	v_sub_f32_e32 v2, v2, v6
	v_sub_f32_e32 v8, v8, v6
	v_sub_f32_e32 v3, v3, v6
	v_sub_f32_e32 v9, v9, v6
	v_sub_f32_e32 v4, v4, v6
	v_sub_f32_e32 v10, v10, v6
	v_sub_f32_e32 v5, v5, v6
	v_mul_f32_e32 v2, v7, v2
	v_mul_f32_e32 v8, v7, v8
	v_mul_f32_e32 v3, v7, v3
	v_mul_f32_e32 v9, v7, v9
	v_mul_f32_e32 v4, v7, v4
	v_mul_f32_e32 v10, v7, v10
	v_mul_f32_e32 v5, v7, v5
	v_xor_b32_e32 v6, v69, v73
	v_lshlrev_b32_e32 v6, 1, v6
	v_bfe_u32 v7, v0, 16, 1
	v_mul_f32_e32 v2, v23, v2
	v_add3_u32 v0, v0, v7, s90
	v_add3_u32 v6, 0, v6, v32
	ds_write_b16_d16_hi v6, v0 offset:34816
	v_bfe_u32 v0, v2, 16, 1
	v_mul_f32_e32 v8, v24, v8
	v_add3_u32 v0, v2, v0, s90
	ds_write_b16_d16_hi v6, v0 offset:35088
	v_bfe_u32 v0, v8, 16, 1
	v_mul_f32_e32 v3, v25, v3
	v_add3_u32 v0, v8, v0, s90
	ds_write_b16_d16_hi v6, v0 offset:35360
	v_bfe_u32 v0, v3, 16, 1
	v_mul_f32_e32 v9, v18, v9
	v_add3_u32 v0, v3, v0, s90
	ds_write_b16_d16_hi v6, v0 offset:35632
	v_bfe_u32 v0, v9, 16, 1
	v_mul_f32_e32 v4, v19, v4
	v_add3_u32 v0, v9, v0, s90
	ds_write_b16_d16_hi v6, v0 offset:35904
	v_bfe_u32 v0, v4, 16, 1
	v_mul_f32_e32 v10, v20, v10
	v_add3_u32 v0, v4, v0, s90
	ds_write_b16_d16_hi v6, v0 offset:36176
	v_bfe_u32 v0, v10, 16, 1
	v_mul_f32_e32 v5, v21, v5
	v_add3_u32 v0, v10, v0, s90
	ds_write_b16_d16_hi v6, v0 offset:36448
	v_bfe_u32 v0, v5, 16, 1
	v_add3_u32 v0, v5, v0, s90
	ds_write_b16_d16_hi v6, v0 offset:36720
	v_bfe_u32 v18, v68, 4, 2
	v_bfi_b32 v0, -16, v72, v68
	v_and_b32_e32 v200, 0x18, v0
	v_lshrrev_b32_e32 v201, 5, v0
	v_lshlrev_b32_e32 v200, 1, v200
	v_and_b32_e32 v201, 3, v201
	v_and_b32_e32 v19, -16, v72
	v_mul_lo_u32 v0, v0, s14
	v_lshlrev_b32_e32 v22, 4, v18
	v_lshlrev_b32_e32 v201, 6, v201
	v_xor_b32_e32 v200, v22, v200
	v_add3_u32 v0, 0, v0, v200
	v_xor_b32_e32 v203, 64, v201
	v_xor_b32_e32 v204, 0x80, v201
	v_xor_b32_e32 v205, 0xc0, v201
	v_add_u32_e32 v202, v0, v201
	v_add_u32_e32 v203, v0, v203
	v_add_u32_e32 v204, v0, v204
	v_add_u32_e32 v205, v0, v205
	v_lshl_or_b32 v18, v18, 2, v19
	s_waitcnt lgkmcnt(0)
	s_barrier
	v_and_b32_e32 v23, 15, v68
	ds_read_b128 v[2:5], v202 offset:34816
	ds_read_b128 v[6:9], v203 offset:34816
	ds_read_b128 v[10:13], v204 offset:34816
	ds_read_b128 v[14:17], v205 offset:34816
	v_mov_b32_e32 v0, s20
	v_ashrrev_i32_e32 v19, 31, v18
	v_lshl_add_u64 v[24:25], v[18:19], 1, v[0:1]
	v_add_lshl_u32 v0, s11, v23, 11
	s_ashr_i32 s12, s6, 31
	v_or_b32_e32 v20, s6, v23
	v_lshl_add_u64 v[18:19], v[24:25], 0, v[0:1]
	v_mul_u32_u24_e32 v0, 0x110, v23
	s_add_i32 s6, s16, s7
	v_add3_u32 v26, v0, v22, 0
	v_add_u32_e32 v22, s6, v23
	s_lshl_b32 s6, s10, 16
	s_and_b32 s6, s6, 0x3fc0000
	v_mov_b32_e32 v21, s12
	v_lshl_or_b32 v0, v23, 11, s6
	v_lshl_add_u64 v[20:21], v[20:21], 2, s[8:9]
	v_lshl_add_u64 v[24:25], v[24:25], 0, v[0:1]
	v_lshl_add_u64 v[18:19], s[64:65], 0, v[18:19]
	v_lshl_add_u64 v[20:21], v[20:21], 0, 64
	v_lshl_add_u64 v[24:25], s[64:65], 0, v[24:25]
	s_mov_b64 s[6:7], 0
.LBB0_250:
	s_mov_b32 s100, 0xed00000
	s_mov_b32 s101, 0
	ds_read_b128 v[104:107], v26 offset:0
	ds_read_b128 v[108:111], v26 offset:64
	ds_read_b128 v[112:115], v26 offset:128
	ds_read_b128 v[116:119], v26 offset:192
	ds_read_b128 v[120:123], v26 offset:4352
	ds_read_b128 v[124:127], v26 offset:4416
	ds_read_b128 v[128:131], v26 offset:4480
	ds_read_b128 v[132:135], v26 offset:4544
	s_waitcnt lgkmcnt(4)
	v_mfma_f32_16x16x32_bf16 v[136:139], v[2:5], v[104:107], 0
	v_mfma_f32_16x16x32_bf16 v[136:139], v[6:9], v[108:111], v[136:139]
	v_mfma_f32_16x16x32_bf16 v[136:139], v[10:13], v[112:115], v[136:139]
	v_mfma_f32_16x16x32_bf16 v[136:139], v[14:17], v[116:119], v[136:139]
	ds_read_b128 v[104:107], v26 offset:8704
	ds_read_b128 v[108:111], v26 offset:8768
	ds_read_b128 v[112:115], v26 offset:8832
	ds_read_b128 v[116:119], v26 offset:8896
	s_waitcnt vmcnt(0)
	s_waitcnt lgkmcnt(4)
	v_mfma_f32_16x16x32_bf16 v[140:143], v[2:5], v[120:123], 0
	v_mfma_f32_16x16x32_bf16 v[140:143], v[6:9], v[124:127], v[140:143]
	v_mfma_f32_16x16x32_bf16 v[140:143], v[10:13], v[128:131], v[140:143]
	v_mfma_f32_16x16x32_bf16 v[140:143], v[14:17], v[132:135], v[140:143]
	ds_read_b128 v[120:123], v26 offset:13056
	ds_read_b128 v[124:127], v26 offset:13120
	ds_read_b128 v[128:131], v26 offset:13184
	ds_read_b128 v[132:135], v26 offset:13248
	v_add_f32_e32 v148, v136, v80
	v_add_f32_e32 v149, v137, v80
	v_add_f32_e32 v150, v138, v80
	v_add_f32_e32 v151, v139, v80
	v_lshlrev_b32_e32 v152, 16, v88
	v_and_b32_e32 v153, 0xffff0000, v88
	v_lshlrev_b32_e32 v154, 16, v89
	v_and_b32_e32 v155, 0xffff0000, v89
	v_mul_f32_e32 v148, v148, v152
	v_mul_f32_e32 v149, v149, v153
	v_mul_f32_e32 v150, v150, v154
	v_mul_f32_e32 v151, v151, v155
	v_cvt_pk_bf16_f32 v148, v148, v149
	v_cvt_pk_bf16_f32 v149, v150, v151
	v_lshl_add_u64 v[146:147], v[24:25], 0, s[100:101]
	global_store_dwordx2 v[146:147], v[148:149], off offset:1024
	s_waitcnt lgkmcnt(4)
	v_mfma_f32_16x16x32_bf16 v[136:139], v[2:5], v[104:107], 0
	v_mfma_f32_16x16x32_bf16 v[136:139], v[6:9], v[108:111], v[136:139]
	v_mfma_f32_16x16x32_bf16 v[136:139], v[10:13], v[112:115], v[136:139]
	v_mfma_f32_16x16x32_bf16 v[136:139], v[14:17], v[116:119], v[136:139]
	ds_read_b128 v[104:107], v26 offset:17408
	ds_read_b128 v[108:111], v26 offset:17472
	ds_read_b128 v[112:115], v26 offset:17536
	ds_read_b128 v[116:119], v26 offset:17600
	v_add_f32_e32 v148, v140, v81
	v_add_f32_e32 v149, v141, v81
	v_add_f32_e32 v150, v142, v81
	v_add_f32_e32 v151, v143, v81
	v_lshlrev_b32_e32 v152, 16, v90
	v_and_b32_e32 v153, 0xffff0000, v90
	v_lshlrev_b32_e32 v154, 16, v91
	v_and_b32_e32 v155, 0xffff0000, v91
	v_mul_f32_e32 v148, v148, v152
	v_mul_f32_e32 v149, v149, v153
	v_mul_f32_e32 v150, v150, v154
	v_mul_f32_e32 v151, v151, v155
	v_cvt_pk_bf16_f32 v148, v148, v149
	v_cvt_pk_bf16_f32 v149, v150, v151
	v_lshl_add_u64 v[146:147], v[18:19], 0, s[100:101]
	global_store_dwordx2 v[146:147], v[148:149], off offset:1024
	s_add_u32 s100, s100, 0x10000
	s_waitcnt lgkmcnt(4)
	v_mfma_f32_16x16x32_bf16 v[140:143], v[2:5], v[120:123], 0
	v_mfma_f32_16x16x32_bf16 v[140:143], v[6:9], v[124:127], v[140:143]
	v_mfma_f32_16x16x32_bf16 v[140:143], v[10:13], v[128:131], v[140:143]
	v_mfma_f32_16x16x32_bf16 v[140:143], v[14:17], v[132:135], v[140:143]
	ds_read_b128 v[120:123], v26 offset:21760
	ds_read_b128 v[124:127], v26 offset:21824
	ds_read_b128 v[128:131], v26 offset:21888
	ds_read_b128 v[132:135], v26 offset:21952
	v_add_f32_e32 v148, v136, v82
	v_add_f32_e32 v149, v137, v82
	v_add_f32_e32 v150, v138, v82
	v_add_f32_e32 v151, v139, v82
	v_lshlrev_b32_e32 v152, 16, v92
	v_and_b32_e32 v153, 0xffff0000, v92
	v_lshlrev_b32_e32 v154, 16, v93
	v_and_b32_e32 v155, 0xffff0000, v93
	v_mul_f32_e32 v148, v148, v152
	v_mul_f32_e32 v149, v149, v153
	v_mul_f32_e32 v150, v150, v154
	v_mul_f32_e32 v151, v151, v155
	v_cvt_pk_bf16_f32 v148, v148, v149
	v_cvt_pk_bf16_f32 v149, v150, v151
	v_lshl_add_u64 v[146:147], v[24:25], 0, s[100:101]
	global_store_dwordx2 v[146:147], v[148:149], off offset:1024
	s_waitcnt lgkmcnt(4)
	v_mfma_f32_16x16x32_bf16 v[136:139], v[2:5], v[104:107], 0
	v_mfma_f32_16x16x32_bf16 v[136:139], v[6:9], v[108:111], v[136:139]
	v_mfma_f32_16x16x32_bf16 v[136:139], v[10:13], v[112:115], v[136:139]
	v_mfma_f32_16x16x32_bf16 v[136:139], v[14:17], v[116:119], v[136:139]
	ds_read_b128 v[104:107], v26 offset:26112
	ds_read_b128 v[108:111], v26 offset:26176
	ds_read_b128 v[112:115], v26 offset:26240
	ds_read_b128 v[116:119], v26 offset:26304
	v_add_f32_e32 v148, v140, v83
	v_add_f32_e32 v149, v141, v83
	v_add_f32_e32 v150, v142, v83
	v_add_f32_e32 v151, v143, v83
	v_lshlrev_b32_e32 v152, 16, v94
	v_and_b32_e32 v153, 0xffff0000, v94
	v_lshlrev_b32_e32 v154, 16, v95
	v_and_b32_e32 v155, 0xffff0000, v95
	v_mul_f32_e32 v148, v148, v152
	v_mul_f32_e32 v149, v149, v153
	v_mul_f32_e32 v150, v150, v154
	v_mul_f32_e32 v151, v151, v155
	v_cvt_pk_bf16_f32 v148, v148, v149
	v_cvt_pk_bf16_f32 v149, v150, v151
	v_lshl_add_u64 v[146:147], v[18:19], 0, s[100:101]
	global_store_dwordx2 v[146:147], v[148:149], off offset:1024
	s_add_u32 s100, s100, 0x10000
	s_waitcnt lgkmcnt(4)
	v_mfma_f32_16x16x32_bf16 v[140:143], v[2:5], v[120:123], 0
	v_mfma_f32_16x16x32_bf16 v[140:143], v[6:9], v[124:127], v[140:143]
	v_mfma_f32_16x16x32_bf16 v[140:143], v[10:13], v[128:131], v[140:143]
	v_mfma_f32_16x16x32_bf16 v[140:143], v[14:17], v[132:135], v[140:143]
	ds_read_b128 v[120:123], v26 offset:30464
	ds_read_b128 v[124:127], v26 offset:30528
	ds_read_b128 v[128:131], v26 offset:30592
	ds_read_b128 v[132:135], v26 offset:30656
	v_add_f32_e32 v148, v136, v84
	v_add_f32_e32 v149, v137, v84
	v_add_f32_e32 v150, v138, v84
	v_add_f32_e32 v151, v139, v84
	v_lshlrev_b32_e32 v152, 16, v96
	v_and_b32_e32 v153, 0xffff0000, v96
	v_lshlrev_b32_e32 v154, 16, v97
	v_and_b32_e32 v155, 0xffff0000, v97
	v_mul_f32_e32 v148, v148, v152
	v_mul_f32_e32 v149, v149, v153
	v_mul_f32_e32 v150, v150, v154
	v_mul_f32_e32 v151, v151, v155
	v_cvt_pk_bf16_f32 v148, v148, v149
	v_cvt_pk_bf16_f32 v149, v150, v151
	v_lshl_add_u64 v[146:147], v[24:25], 0, s[100:101]
	global_store_dwordx2 v[146:147], v[148:149], off offset:1024
	s_waitcnt lgkmcnt(4)
	v_mfma_f32_16x16x32_bf16 v[136:139], v[2:5], v[104:107], 0
	v_mfma_f32_16x16x32_bf16 v[136:139], v[6:9], v[108:111], v[136:139]
	v_mfma_f32_16x16x32_bf16 v[136:139], v[10:13], v[112:115], v[136:139]
	v_mfma_f32_16x16x32_bf16 v[136:139], v[14:17], v[116:119], v[136:139]
	v_add_f32_e32 v148, v140, v85
	v_add_f32_e32 v149, v141, v85
	v_add_f32_e32 v150, v142, v85
	v_add_f32_e32 v151, v143, v85
	v_lshlrev_b32_e32 v152, 16, v98
	v_and_b32_e32 v153, 0xffff0000, v98
	v_lshlrev_b32_e32 v154, 16, v99
	v_and_b32_e32 v155, 0xffff0000, v99
	v_mul_f32_e32 v148, v148, v152
	v_mul_f32_e32 v149, v149, v153
	v_mul_f32_e32 v150, v150, v154
	v_mul_f32_e32 v151, v151, v155
	v_cvt_pk_bf16_f32 v148, v148, v149
	v_cvt_pk_bf16_f32 v149, v150, v151
	v_lshl_add_u64 v[146:147], v[18:19], 0, s[100:101]
	global_store_dwordx2 v[146:147], v[148:149], off offset:1024
	s_add_u32 s100, s100, 0x10000
	s_waitcnt lgkmcnt(0)
	v_mfma_f32_16x16x32_bf16 v[140:143], v[2:5], v[120:123], 0
	v_mfma_f32_16x16x32_bf16 v[140:143], v[6:9], v[124:127], v[140:143]
	v_mfma_f32_16x16x32_bf16 v[140:143], v[10:13], v[128:131], v[140:143]
	v_mfma_f32_16x16x32_bf16 v[140:143], v[14:17], v[132:135], v[140:143]
	v_add_f32_e32 v148, v136, v86
	v_add_f32_e32 v149, v137, v86
	v_add_f32_e32 v150, v138, v86
	v_add_f32_e32 v151, v139, v86
	v_lshlrev_b32_e32 v152, 16, v100
	v_and_b32_e32 v153, 0xffff0000, v100
	v_lshlrev_b32_e32 v154, 16, v101
	v_and_b32_e32 v155, 0xffff0000, v101
	v_mul_f32_e32 v148, v148, v152
	v_mul_f32_e32 v149, v149, v153
	v_mul_f32_e32 v150, v150, v154
	v_mul_f32_e32 v151, v151, v155
	v_cvt_pk_bf16_f32 v148, v148, v149
	v_cvt_pk_bf16_f32 v149, v150, v151
	v_lshl_add_u64 v[146:147], v[24:25], 0, s[100:101]
	global_store_dwordx2 v[146:147], v[148:149], off offset:1024
	s_nop 7
	s_nop 1
	v_add_f32_e32 v148, v140, v87
	v_add_f32_e32 v149, v141, v87
	v_add_f32_e32 v150, v142, v87
	v_add_f32_e32 v151, v143, v87
	v_lshlrev_b32_e32 v152, 16, v102
	v_and_b32_e32 v153, 0xffff0000, v102
	v_lshlrev_b32_e32 v154, 16, v103
	v_and_b32_e32 v155, 0xffff0000, v103
	v_mul_f32_e32 v148, v148, v152
	v_mul_f32_e32 v149, v149, v153
	v_mul_f32_e32 v150, v150, v154
	v_mul_f32_e32 v151, v151, v155
	v_cvt_pk_bf16_f32 v148, v148, v149
	v_cvt_pk_bf16_f32 v149, v150, v151
	v_lshl_add_u64 v[146:147], v[18:19], 0, s[100:101]
	global_store_dwordx2 v[146:147], v[148:149], off offset:1024
	s_barrier
	s_branch .LBB0_245
